# grid barriers: each workgroup L1-invalidate issued at arrival (overlapping the arrival atomic) instead of after release
# speedup vs baseline: 1.0419x; 1.0089x over previous
; #define LAS __attribute__((address_space(3)))
; __device__ __forceinline__ int get_tid() { int t = __builtin_amdgcn_workitem_id_x(); asm volatile("" : "+v"(t)); return t; }
; __device__ __forceinline__ unsigned xb_ld(unsigned* p)              { return __hip_atomic_load(p, __ATOMIC_RELAXED, __HIP_MEMORY_SCOPE_AGENT); }
; __device__ __forceinline__ unsigned xb_xcc_id() { return (unsigned)__builtin_amdgcn_s_getreg((3 << 11) | 20) & 0xFu; }
; __device__ __forceinline__ void xcd_barrier_complete(unsigned* bar, unsigned x, unsigned& nloc, unsigned& nx) {
;     ...
;     for (;;) {
;         sum = 0u; cnt = 0u; mine = 0u;
; #pragma unroll
;         for (unsigned j = 0; j < 16; ++j) { const unsigned c = xb_ld(&bar[XB_XCNT(j)]); sum += c; cnt += (c > 0u) ? 1u : 0u; mine = (j == x) ? c : mine; }
;         if (sum == G) break;
;         __builtin_amdgcn_s_sleep(1);
;         if ((++sp & 255u) == 0u) { if (xb_ld(&bar[XB_TMO])) break; if (sp > XB_SPIN_CAP) { atomicAdd(&bar[XB_TMO], 1u); break; } }
;     }
;     nloc = mine > 0u ? mine : 1u; nx = cnt > 0u ? cnt : 1u;
; __device__ __forceinline__ void xcd_barrier(unsigned* bar, volatile LAS unsigned* st) {
;     asm volatile("s_waitcnt vmcnt(0)" ::: "memory");
;     __syncthreads();
;     if (get_tid() == 0) {
;         const unsigned x = xb_xcc_id();
;         __builtin_amdgcn_s_waitcnt(0);
;         unsigned nloc = st[0], nx = st[1];
;         if (nloc == 0u) { xcd_barrier_complete(bar, x, nloc, nx); st[0] = nloc; st[1] = nx; }
.LBB0_386:
	s_mov_b64 s[2:3], s[0:1]
	s_load_dword s4, s[2:3], 0xd8
	s_mov_b32 s11, 0
	s_waitcnt lgkmcnt(0)
	s_cmp_gt_i32 s4, 0
	s_cbranch_scc1 .LBB0_399
	s_load_dword s2, s[2:3], 0xdc
	s_waitcnt lgkmcnt(0)
	s_cmp_lt_i32 s2, 2
	s_cbranch_scc1 .LBB0_399
	v_mov_b32_e32 v161, 0
	v_mov_b32_e32 v254, 1
	s_add_i32 s2, 0, 0x25c00
	v_writelane_b32 v255, s2, 0
	s_add_i32 s2, 0, 0x25c04
	v_writelane_b32 v255, s2, 1
	s_mov_b64 s[4:5], s[0:1]
	s_add_u32 s28, s0, 0xe0
	s_addc_u32 s29, s1, 0
	s_waitcnt vmcnt(0)
	s_waitcnt vmcnt(0)
	v_mov_b32_e32 v0, v206
	s_barrier
	s_nop 0
	v_cmp_eq_u32_e32 vcc, 0, v0
	s_and_saveexec_b64 s[2:3], vcc
	s_cbranch_execz .Lmyb0_662
	buffer_inv sc1
	v_readlane_b32 s7, v255, 0
	s_load_dwordx2 s[4:5], s[4:5], 0xd0
	s_getreg_b32 s6, hwreg(HW_REG_XCC_ID, 0, 4)
	v_mov_b32_e32 v0, s7
	s_waitcnt lgkmcnt(0)
	ds_read_b32 v2, v0
	v_readlane_b32 s7, v255, 1
	s_and_b32 s10, s6, 15
	s_waitcnt lgkmcnt(0)
	v_cmp_ne_u32_e32 vcc, 0, v2
	v_mov_b32_e32 v0, s7
	ds_read_b32 v0, v0
	s_cbranch_vccnz .Lmyb0_626
	s_add_u32 s6, s4, 0x4200
	s_addc_u32 s7, s5, 0
	s_add_u32 s12, s4, 0x4400
	s_addc_u32 s13, s5, 0
	s_add_u32 s14, s4, 0x4500
	s_addc_u32 s15, s5, 0
	s_add_u32 s16, s4, 0x4600
	s_addc_u32 s17, s5, 0
	s_add_u32 s18, s4, 0x4700
	s_addc_u32 s19, s5, 0
	s_add_u32 s20, s4, 0x4800
	s_addc_u32 s21, s5, 0
	s_add_u32 s22, s4, 0x4900
	s_addc_u32 s23, s5, 0
	s_add_u32 s24, s4, 0x4a00
	s_addc_u32 s25, s5, 0
	s_add_u32 s26, s4, 0x4b00
	s_addc_u32 s27, s5, 0
	s_add_u32 s68, s4, 0x4c00
	s_addc_u32 s69, s5, 0
	s_add_u32 s70, s4, 0x4d00
	s_addc_u32 s71, s5, 0
	s_add_u32 s72, s4, 0x4e00
	s_addc_u32 s73, s5, 0
	s_add_u32 s74, s4, 0x4f00
	s_addc_u32 s75, s5, 0
	s_add_u32 s76, s4, 0x5000
	s_addc_u32 s77, s5, 0
	s_add_u32 s78, s4, 0x5100
	s_addc_u32 s79, s5, 0
	s_add_u32 s80, s4, 0x5200
	s_addc_u32 s81, s5, 0
	s_add_u32 s82, s4, 0x5300
	s_addc_u32 s83, s5, 0
	s_mov_b32 s31, 1
	s_branch .Lmyb0_614

; __device__ __forceinline__ unsigned xb_ld(unsigned* p)              { return __hip_atomic_load(p, __ATOMIC_RELAXED, __HIP_MEMORY_SCOPE_AGENT); }
; __device__ __forceinline__ unsigned xb_add(unsigned* p, unsigned v) { return __hip_atomic_fetch_add(p, v, __ATOMIC_RELAXED, __HIP_MEMORY_SCOPE_AGENT); }
; #define XB_SPIN(cond, bar) do { unsigned _sp = 0; while (cond) { __builtin_amdgcn_s_sleep(1); \
;     if ((++_sp & 255u) == 0u) { if (xb_ld(&(bar)[XB_TMO])) break; if (_sp > XB_SPIN_CAP) { atomicAdd(&(bar)[XB_TMO], 1u); break; } } } } while (0)
; __device__ __forceinline__ void xcd_barrier(unsigned* bar, volatile LAS unsigned* st) {
;     ...
;             else XB_SPIN(xb_ld(&bar[XB_TOPGEN]) == tg, bar);
;             __builtin_amdgcn_fence(__ATOMIC_ACQUIRE, "agent");
;             xb_add(&bar[XB_XGEN(x)], 1u);
;             asm volatile("s_waitcnt vmcnt(0)" ::: "memory");
;         } else {
;             XB_SPIN(xb_ld(&bar[XB_XGEN(x)]) == gen, bar);
;             __builtin_amdgcn_fence(__ATOMIC_ACQUIRE, "agent");
;             asm volatile("s_waitcnt vmcnt(0)" ::: "memory");
;         }
.Lmyb0_641:
	s_or_b64 exec, exec, s[14:15]
	s_waitcnt vmcnt(0)
	s_waitcnt vmcnt(0)

; __device__ __forceinline__ unsigned xb_ld(unsigned* p)              { return __hip_atomic_load(p, __ATOMIC_RELAXED, __HIP_MEMORY_SCOPE_AGENT); }
; __device__ __forceinline__ unsigned xb_add(unsigned* p, unsigned v) { return __hip_atomic_fetch_add(p, v, __ATOMIC_RELAXED, __HIP_MEMORY_SCOPE_AGENT); }
; #define XB_SPIN(cond, bar) do { unsigned _sp = 0; while (cond) { __builtin_amdgcn_s_sleep(1); \
;     if ((++_sp & 255u) == 0u) { if (xb_ld(&(bar)[XB_TMO])) break; if (_sp > XB_SPIN_CAP) { atomicAdd(&(bar)[XB_TMO], 1u); break; } } } } while (0)
; __device__ __forceinline__ void xcd_barrier(unsigned* bar, volatile LAS unsigned* st) {
;     ...
;         const unsigned old = xb_add(&bar[XB_XSUB(x)], 1u);
;         const unsigned gen = old / nloc;
;         if (old + 1u == (gen + 1u) * nloc) {
;             __builtin_amdgcn_fence(__ATOMIC_RELEASE, "agent");
;             asm volatile("s_waitcnt vmcnt(0)" ::: "memory");
;             const unsigned og = xb_add(&bar[XB_TOP], 1u);
;             const unsigned tg = og / nx;
;             if (og + 1u == (tg + 1u) * nx) xb_add(&bar[XB_TOPGEN], 1u);
;             else XB_SPIN(xb_ld(&bar[XB_TOPGEN]) == tg, bar);
;             __builtin_amdgcn_fence(__ATOMIC_ACQUIRE, "agent");
;             xb_add(&bar[XB_XGEN(x)], 1u);
;             asm volatile("s_waitcnt vmcnt(0)" ::: "memory");
.Lmyb0_659:
	s_or_b64 exec, exec, s[4:5]
	s_mov_b64 s[4:5], exec
	v_mbcnt_lo_u32_b32 v0, s4, 0
	v_mbcnt_hi_u32_b32 v0, s5, v0
	v_cmp_eq_u32_e32 vcc, 0, v0
	s_waitcnt vmcnt(0)
	s_and_saveexec_b64 s[12:13], vcc
	s_cbranch_execz .Lmyb0_661
	s_bcnt1_i32_b64 s4, s[4:5]
	v_mov_b32_e32 v0, s4
	v_mov_b32_e32 v1, 0x2000
	global_atomic_add v1, v0, s[6:7] offset:1024

; #define LAS __attribute__((address_space(3)))
; __device__ __forceinline__ int get_tid() { int t = __builtin_amdgcn_workitem_id_x(); asm volatile("" : "+v"(t)); return t; }
; __device__ __forceinline__ unsigned xb_xcc_id() { return (unsigned)__builtin_amdgcn_s_getreg((3 << 11) | 20) & 0xFu; }
; __device__ __forceinline__ void xcd_barrier(unsigned* bar, volatile LAS unsigned* st) {
;     asm volatile("s_waitcnt vmcnt(0)" ::: "memory");
;     __syncthreads();
;     if (get_tid() == 0) {
;         const unsigned x = xb_xcc_id();
;         __builtin_amdgcn_s_waitcnt(0);
;         unsigned nloc = st[0], nx = st[1];
;         if (nloc == 0u) { xcd_barrier_complete(bar, x, nloc, nx); st[0] = nloc; st[1] = nx; }
.LBB0_608:
	s_mov_b64 s[4:5], s[0:1]
	s_load_dword s2, s[4:5], 0xd8
	s_add_i32 s54, s87, 2
	v_writelane_b32 v255, s87, 9
	s_waitcnt lgkmcnt(0)
	s_cmp_gt_i32 s2, s31
	s_cbranch_scc1 .LBB0_663
	s_load_dword s2, s[4:5], 0xdc
	s_waitcnt lgkmcnt(0)
	s_cmp_ge_i32 s54, s2
	s_cbranch_scc1 .LBB0_663
	s_waitcnt vmcnt(0)
	s_waitcnt vmcnt(0)
	v_mov_b32_e32 v0, v206
	s_barrier
	s_nop 0
	v_cmp_eq_u32_e32 vcc, 0, v0
	s_and_saveexec_b64 s[2:3], vcc
	s_cbranch_execz .LBB0_662
	buffer_inv sc1
	v_readlane_b32 s7, v255, 0
	s_load_dwordx2 s[4:5], s[4:5], 0xd0
	s_getreg_b32 s6, hwreg(HW_REG_XCC_ID, 0, 4)
	v_mov_b32_e32 v0, s7
	s_waitcnt lgkmcnt(0)
	ds_read_b32 v2, v0
	v_readlane_b32 s7, v255, 1
	s_and_b32 s10, s6, 15
	s_waitcnt lgkmcnt(0)
	v_cmp_ne_u32_e32 vcc, 0, v2
	v_mov_b32_e32 v0, s7
	ds_read_b32 v0, v0
	s_cbranch_vccnz .LBB0_626
	s_add_u32 s6, s4, 0x4200
	s_addc_u32 s7, s5, 0
	s_add_u32 s12, s4, 0x4400
	s_addc_u32 s13, s5, 0
	s_add_u32 s14, s4, 0x4500
	s_addc_u32 s15, s5, 0
	s_add_u32 s16, s4, 0x4600
	s_addc_u32 s17, s5, 0
	s_add_u32 s18, s4, 0x4700
	s_addc_u32 s19, s5, 0
	s_add_u32 s20, s4, 0x4800
	s_addc_u32 s21, s5, 0
	s_add_u32 s22, s4, 0x4900
	s_addc_u32 s23, s5, 0
	s_add_u32 s24, s4, 0x4a00
	s_addc_u32 s25, s5, 0
	s_add_u32 s26, s4, 0x4b00
	s_addc_u32 s27, s5, 0
	s_add_u32 s68, s4, 0x4c00
	s_addc_u32 s69, s5, 0
	s_add_u32 s70, s4, 0x4d00
	s_addc_u32 s71, s5, 0
	s_add_u32 s72, s4, 0x4e00
	s_addc_u32 s73, s5, 0
	s_add_u32 s74, s4, 0x4f00
	s_addc_u32 s75, s5, 0
	s_add_u32 s76, s4, 0x5000
	s_addc_u32 s77, s5, 0
	s_add_u32 s78, s4, 0x5100
	s_addc_u32 s79, s5, 0
	s_add_u32 s80, s4, 0x5200
	s_addc_u32 s81, s5, 0
	s_add_u32 s82, s4, 0x5300
	s_addc_u32 s83, s5, 0
	s_mov_b32 s31, 1
	s_branch .LBB0_614

; #define LAS __attribute__((address_space(3)))
; __device__ __forceinline__ int get_tid() { int t = __builtin_amdgcn_workitem_id_x(); asm volatile("" : "+v"(t)); return t; }
; __device__ __forceinline__ unsigned xb_xcc_id() { return (unsigned)__builtin_amdgcn_s_getreg((3 << 11) | 20) & 0xFu; }
; __device__ __forceinline__ void xcd_barrier(unsigned* bar, volatile LAS unsigned* st) {
;     asm volatile("s_waitcnt vmcnt(0)" ::: "memory");
;     __syncthreads();
;     if (get_tid() == 0) {
;         const unsigned x = xb_xcc_id();
;         __builtin_amdgcn_s_waitcnt(0);
;         unsigned nloc = st[0], nx = st[1];
;         if (nloc == 0u) { xcd_barrier_complete(bar, x, nloc, nx); st[0] = nloc; st[1] = nx; }
.LBB0_1102:
	s_mov_b64 s[4:5], s[0:1]
	s_load_dword s2, s[4:5], 0xd8
	s_add_i32 s31, s87, 3
	s_waitcnt lgkmcnt(0)
	s_cmp_gt_i32 s2, s54
	s_cbranch_scc1 .LBB0_1157
	s_load_dword s2, s[4:5], 0xdc
	s_waitcnt lgkmcnt(0)
	s_cmp_ge_i32 s31, s2
	s_cbranch_scc1 .LBB0_1157
	s_waitcnt vmcnt(0)
	s_waitcnt vmcnt(0)
	v_mov_b32_e32 v0, v206
	s_waitcnt vmcnt(0)
	s_barrier
	s_nop 0
	v_cmp_eq_u32_e32 vcc, 0, v0
	s_and_saveexec_b64 s[2:3], vcc
	s_cbranch_execz .LBB0_1156
	buffer_inv sc1
	v_readlane_b32 s7, v255, 0
	s_load_dwordx2 s[4:5], s[4:5], 0xd0
	s_getreg_b32 s6, hwreg(HW_REG_XCC_ID, 0, 4)
	v_mov_b32_e32 v0, s7
	s_waitcnt lgkmcnt(0)
	ds_read_b32 v2, v0
	v_readlane_b32 s7, v255, 1
	s_and_b32 s10, s6, 15
	s_waitcnt lgkmcnt(0)
	v_cmp_ne_u32_e32 vcc, 0, v2
	v_mov_b32_e32 v0, s7
	ds_read_b32 v0, v0
	s_cbranch_vccnz .LBB0_1120
	s_add_u32 s6, s4, 0x4200
	s_addc_u32 s7, s5, 0
	s_add_u32 s12, s4, 0x4400
	s_addc_u32 s13, s5, 0
	s_add_u32 s14, s4, 0x4500
	s_addc_u32 s15, s5, 0
	s_add_u32 s16, s4, 0x4600
	s_addc_u32 s17, s5, 0
	s_add_u32 s18, s4, 0x4700
	s_addc_u32 s19, s5, 0
	s_add_u32 s20, s4, 0x4800
	s_addc_u32 s21, s5, 0
	s_add_u32 s22, s4, 0x4900
	s_addc_u32 s23, s5, 0
	s_add_u32 s24, s4, 0x4a00
	s_addc_u32 s25, s5, 0
	s_add_u32 s26, s4, 0x4b00
	s_addc_u32 s27, s5, 0
	s_add_u32 s68, s4, 0x4c00
	s_addc_u32 s69, s5, 0
	s_add_u32 s70, s4, 0x4d00
	s_addc_u32 s71, s5, 0
	s_add_u32 s72, s4, 0x4e00
	s_addc_u32 s73, s5, 0
	s_add_u32 s74, s4, 0x4f00
	s_addc_u32 s75, s5, 0
	s_add_u32 s76, s4, 0x5000
	s_addc_u32 s77, s5, 0
	s_add_u32 s78, s4, 0x5100
	s_addc_u32 s79, s5, 0
	s_add_u32 s80, s4, 0x5200
	s_addc_u32 s81, s5, 0
	s_add_u32 s82, s4, 0x5300
	s_addc_u32 s83, s5, 0
	s_mov_b32 s35, 1
	s_branch .LBB0_1108

; #define LAS __attribute__((address_space(3)))
; __device__ __forceinline__ int get_tid() { int t = __builtin_amdgcn_workitem_id_x(); asm volatile("" : "+v"(t)); return t; }
; __device__ __forceinline__ unsigned xb_xcc_id() { return (unsigned)__builtin_amdgcn_s_getreg((3 << 11) | 20) & 0xFu; }
; __device__ __forceinline__ void xcd_barrier(unsigned* bar, volatile LAS unsigned* st) {
;     asm volatile("s_waitcnt vmcnt(0)" ::: "memory");
;     __syncthreads();
;     if (get_tid() == 0) {
;         const unsigned x = xb_xcc_id();
;         __builtin_amdgcn_s_waitcnt(0);
;         unsigned nloc = st[0], nx = st[1];
;         if (nloc == 0u) { xcd_barrier_complete(bar, x, nloc, nx); st[0] = nloc; st[1] = nx; }
.LBB0_1252:
	s_mov_b64 s[4:5], s[0:1]
	s_load_dword s2, s[4:5], 0xd8
	s_add_i32 s54, s87, 4
	s_waitcnt lgkmcnt(0)
	s_cmp_gt_i32 s2, s31
	s_cbranch_scc1 .LBB0_1307
	s_load_dword s2, s[4:5], 0xdc
	s_waitcnt lgkmcnt(0)
	s_cmp_ge_i32 s54, s2
	s_cbranch_scc1 .LBB0_1307
	s_waitcnt vmcnt(0)
	s_waitcnt vmcnt(0)
	v_mov_b32_e32 v0, v206
	s_waitcnt vmcnt(0)
	s_barrier
	s_nop 0
	v_cmp_eq_u32_e32 vcc, 0, v0
	s_and_saveexec_b64 s[2:3], vcc
	s_cbranch_execz .LBB0_1306
	buffer_inv sc1
	v_readlane_b32 s7, v255, 0
	s_load_dwordx2 s[4:5], s[4:5], 0xd0
	s_getreg_b32 s6, hwreg(HW_REG_XCC_ID, 0, 4)
	v_mov_b32_e32 v0, s7
	s_waitcnt lgkmcnt(0)
	ds_read_b32 v2, v0
	v_readlane_b32 s7, v255, 1
	s_and_b32 s10, s6, 15
	s_waitcnt lgkmcnt(0)
	v_cmp_ne_u32_e32 vcc, 0, v2
	v_mov_b32_e32 v0, s7
	ds_read_b32 v0, v0
	s_cbranch_vccnz .LBB0_1270
	s_add_u32 s6, s4, 0x4200
	s_addc_u32 s7, s5, 0
	s_add_u32 s12, s4, 0x4400
	s_addc_u32 s13, s5, 0
	s_add_u32 s14, s4, 0x4500
	s_addc_u32 s15, s5, 0
	s_add_u32 s16, s4, 0x4600
	s_addc_u32 s17, s5, 0
	s_add_u32 s18, s4, 0x4700
	s_addc_u32 s19, s5, 0
	s_add_u32 s20, s4, 0x4800
	s_addc_u32 s21, s5, 0
	s_add_u32 s22, s4, 0x4900
	s_addc_u32 s23, s5, 0
	s_add_u32 s24, s4, 0x4a00
	s_addc_u32 s25, s5, 0
	s_add_u32 s26, s4, 0x4b00
	s_addc_u32 s27, s5, 0
	s_add_u32 s68, s4, 0x4c00
	s_addc_u32 s69, s5, 0
	s_add_u32 s70, s4, 0x4d00
	s_addc_u32 s71, s5, 0
	s_add_u32 s72, s4, 0x4e00
	s_addc_u32 s73, s5, 0
	s_add_u32 s74, s4, 0x4f00
	s_addc_u32 s75, s5, 0
	s_add_u32 s76, s4, 0x5000
	s_addc_u32 s77, s5, 0
	s_add_u32 s78, s4, 0x5100
	s_addc_u32 s79, s5, 0
	s_add_u32 s80, s4, 0x5200
	s_addc_u32 s81, s5, 0
	s_add_u32 s82, s4, 0x5300
	s_addc_u32 s83, s5, 0
	s_mov_b32 s31, 1
	s_branch .LBB0_1258

; #define LAS __attribute__((address_space(3)))
; __device__ __forceinline__ int get_tid() { int t = __builtin_amdgcn_workitem_id_x(); asm volatile("" : "+v"(t)); return t; }
; __device__ __forceinline__ unsigned xb_xcc_id() { return (unsigned)__builtin_amdgcn_s_getreg((3 << 11) | 20) & 0xFu; }
; __device__ __forceinline__ void xcd_barrier(unsigned* bar, volatile LAS unsigned* st) {
;     asm volatile("s_waitcnt vmcnt(0)" ::: "memory");
;     __syncthreads();
;     if (get_tid() == 0) {
;         const unsigned x = xb_xcc_id();
;         __builtin_amdgcn_s_waitcnt(0);
;         unsigned nloc = st[0], nx = st[1];
;         if (nloc == 0u) { xcd_barrier_complete(bar, x, nloc, nx); st[0] = nloc; st[1] = nx; }
.LBB0_1414:
	s_mov_b64 s[4:5], s[0:1]
	s_load_dword s2, s[4:5], 0xd8
	s_add_i32 s31, s87, 5
	s_waitcnt lgkmcnt(0)
	s_cmp_gt_i32 s2, s54
	s_cbranch_scc1 .LBB0_1469
	s_load_dword s2, s[4:5], 0xdc
	s_waitcnt lgkmcnt(0)
	s_cmp_ge_i32 s31, s2
	s_cbranch_scc1 .LBB0_1469
	s_waitcnt vmcnt(0)
	s_waitcnt vmcnt(0)
	v_mov_b32_e32 v0, v206
	s_barrier
	s_nop 0
	v_cmp_eq_u32_e32 vcc, 0, v0
	s_and_saveexec_b64 s[2:3], vcc
	s_cbranch_execz .LBB0_1468
	buffer_inv sc1
	v_readlane_b32 s7, v255, 0
	s_load_dwordx2 s[4:5], s[4:5], 0xd0
	s_getreg_b32 s6, hwreg(HW_REG_XCC_ID, 0, 4)
	v_mov_b32_e32 v0, s7
	s_waitcnt lgkmcnt(0)
	ds_read_b32 v2, v0
	v_readlane_b32 s7, v255, 1
	s_and_b32 s10, s6, 15
	s_waitcnt lgkmcnt(0)
	v_cmp_ne_u32_e32 vcc, 0, v2
	v_mov_b32_e32 v0, s7
	ds_read_b32 v0, v0
	s_cbranch_vccnz .LBB0_1432
	s_add_u32 s6, s4, 0x4200
	s_addc_u32 s7, s5, 0
	s_add_u32 s12, s4, 0x4400
	s_addc_u32 s13, s5, 0
	s_add_u32 s14, s4, 0x4500
	s_addc_u32 s15, s5, 0
	s_add_u32 s16, s4, 0x4600
	s_addc_u32 s17, s5, 0
	s_add_u32 s18, s4, 0x4700
	s_addc_u32 s19, s5, 0
	s_add_u32 s20, s4, 0x4800
	s_addc_u32 s21, s5, 0
	s_add_u32 s22, s4, 0x4900
	s_addc_u32 s23, s5, 0
	s_add_u32 s24, s4, 0x4a00
	s_addc_u32 s25, s5, 0
	s_add_u32 s26, s4, 0x4b00
	s_addc_u32 s27, s5, 0
	s_add_u32 s68, s4, 0x4c00
	s_addc_u32 s69, s5, 0
	s_add_u32 s70, s4, 0x4d00
	s_addc_u32 s71, s5, 0
	s_add_u32 s72, s4, 0x4e00
	s_addc_u32 s73, s5, 0
	s_add_u32 s74, s4, 0x4f00
	s_addc_u32 s75, s5, 0
	s_add_u32 s76, s4, 0x5000
	s_addc_u32 s77, s5, 0
	s_add_u32 s78, s4, 0x5100
	s_addc_u32 s79, s5, 0
	s_add_u32 s80, s4, 0x5200
	s_addc_u32 s81, s5, 0
	s_add_u32 s82, s4, 0x5300
	s_addc_u32 s83, s5, 0
	s_mov_b32 s35, 1
	s_branch .LBB0_1420

; #define LAS __attribute__((address_space(3)))
; __device__ __forceinline__ int get_tid() { int t = __builtin_amdgcn_workitem_id_x(); asm volatile("" : "+v"(t)); return t; }
; __device__ __forceinline__ unsigned xb_xcc_id() { return (unsigned)__builtin_amdgcn_s_getreg((3 << 11) | 20) & 0xFu; }
; __device__ __forceinline__ void xcd_barrier(unsigned* bar, volatile LAS unsigned* st) {
;     asm volatile("s_waitcnt vmcnt(0)" ::: "memory");
;     __syncthreads();
;     if (get_tid() == 0) {
;         const unsigned x = xb_xcc_id();
;         __builtin_amdgcn_s_waitcnt(0);
;         unsigned nloc = st[0], nx = st[1];
;         if (nloc == 0u) { xcd_barrier_complete(bar, x, nloc, nx); st[0] = nloc; st[1] = nx; }
.LBB0_1474:
	s_mov_b64 s[4:5], s[0:1]
	s_load_dword s2, s[4:5], 0xd8
	s_add_i32 s56, s87, 6
	s_waitcnt lgkmcnt(0)
	s_cmp_gt_i32 s2, s31
	s_cbranch_scc1 .LBB0_1529
	s_load_dword s2, s[4:5], 0xdc
	s_waitcnt lgkmcnt(0)
	s_cmp_ge_i32 s56, s2
	s_cbranch_scc1 .LBB0_1529
	s_waitcnt vmcnt(0)
	s_waitcnt vmcnt(0)
	v_mov_b32_e32 v0, v206
	s_barrier
	s_nop 0
	v_cmp_eq_u32_e32 vcc, 0, v0
	s_and_saveexec_b64 s[2:3], vcc
	s_cbranch_execz .LBB0_1528
	buffer_inv sc1
	v_readlane_b32 s7, v255, 0
	s_load_dwordx2 s[4:5], s[4:5], 0xd0
	s_getreg_b32 s6, hwreg(HW_REG_XCC_ID, 0, 4)
	v_mov_b32_e32 v0, s7
	s_waitcnt lgkmcnt(0)
	ds_read_b32 v2, v0
	v_readlane_b32 s7, v255, 1
	s_and_b32 s10, s6, 15
	s_waitcnt lgkmcnt(0)
	v_cmp_ne_u32_e32 vcc, 0, v2
	v_mov_b32_e32 v0, s7
	ds_read_b32 v0, v0
	s_cbranch_vccnz .LBB0_1492
	s_add_u32 s6, s4, 0x4200
	s_addc_u32 s7, s5, 0
	s_add_u32 s12, s4, 0x4400
	s_addc_u32 s13, s5, 0
	s_add_u32 s14, s4, 0x4500
	s_addc_u32 s15, s5, 0
	s_add_u32 s16, s4, 0x4600
	s_addc_u32 s17, s5, 0
	s_add_u32 s18, s4, 0x4700
	s_addc_u32 s19, s5, 0
	s_add_u32 s20, s4, 0x4800
	s_addc_u32 s21, s5, 0
	s_add_u32 s22, s4, 0x4900
	s_addc_u32 s23, s5, 0
	s_add_u32 s24, s4, 0x4a00
	s_addc_u32 s25, s5, 0
	s_add_u32 s26, s4, 0x4b00
	s_addc_u32 s27, s5, 0
	s_add_u32 s68, s4, 0x4c00
	s_addc_u32 s69, s5, 0
	s_add_u32 s70, s4, 0x4d00
	s_addc_u32 s71, s5, 0
	s_add_u32 s72, s4, 0x4e00
	s_addc_u32 s73, s5, 0
	s_add_u32 s74, s4, 0x4f00
	s_addc_u32 s75, s5, 0
	s_add_u32 s76, s4, 0x5000
	s_addc_u32 s77, s5, 0
	s_add_u32 s78, s4, 0x5100
	s_addc_u32 s79, s5, 0
	s_add_u32 s80, s4, 0x5200
	s_addc_u32 s81, s5, 0
	s_add_u32 s82, s4, 0x5300
	s_addc_u32 s83, s5, 0
	s_mov_b32 s31, 1
	s_branch .LBB0_1480

; #define LAS __attribute__((address_space(3)))
; __device__ __forceinline__ int get_tid() { int t = __builtin_amdgcn_workitem_id_x(); asm volatile("" : "+v"(t)); return t; }
; __device__ __forceinline__ unsigned xb_xcc_id() { return (unsigned)__builtin_amdgcn_s_getreg((3 << 11) | 20) & 0xFu; }
; __device__ __forceinline__ void xcd_barrier(unsigned* bar, volatile LAS unsigned* st) {
;     asm volatile("s_waitcnt vmcnt(0)" ::: "memory");
;     __syncthreads();
;     if (get_tid() == 0) {
;         const unsigned x = xb_xcc_id();
;         __builtin_amdgcn_s_waitcnt(0);
;         unsigned nloc = st[0], nx = st[1];
;         if (nloc == 0u) { xcd_barrier_complete(bar, x, nloc, nx); st[0] = nloc; st[1] = nx; }
.Lmy_cvm_done:
.LBB0_1918:
	s_mov_b64 s[4:5], s[0:1]
	s_load_dword s2, s[4:5], 0xd8
	s_add_i32 s31, s87, 7
	s_waitcnt lgkmcnt(0)
	s_cmp_gt_i32 s2, s56
	s_cbranch_scc1 .LBB0_1973
	s_load_dword s2, s[4:5], 0xdc
	s_waitcnt lgkmcnt(0)
	s_cmp_ge_i32 s31, s2
	s_cbranch_scc1 .LBB0_1973
	s_waitcnt vmcnt(0)
	s_waitcnt vmcnt(0)
	v_mov_b32_e32 v0, v206
	s_barrier
	s_nop 0
	v_cmp_eq_u32_e32 vcc, 0, v0
	s_and_saveexec_b64 s[2:3], vcc
	s_cbranch_execz .LBB0_1972
	buffer_inv sc1
	v_readlane_b32 s7, v255, 0
	s_load_dwordx2 s[4:5], s[4:5], 0xd0
	s_getreg_b32 s6, hwreg(HW_REG_XCC_ID, 0, 4)
	v_mov_b32_e32 v0, s7
	s_waitcnt lgkmcnt(0)
	ds_read_b32 v2, v0
	v_readlane_b32 s7, v255, 1
	s_and_b32 s10, s6, 15
	s_waitcnt lgkmcnt(0)
	v_cmp_ne_u32_e32 vcc, 0, v2
	v_mov_b32_e32 v0, s7
	ds_read_b32 v0, v0
	s_cbranch_vccnz .LBB0_1936
	s_add_u32 s6, s4, 0x4200
	s_addc_u32 s7, s5, 0
	s_add_u32 s12, s4, 0x4400
	s_addc_u32 s13, s5, 0
	s_add_u32 s14, s4, 0x4500
	s_addc_u32 s15, s5, 0
	s_add_u32 s16, s4, 0x4600
	s_addc_u32 s17, s5, 0
	s_add_u32 s18, s4, 0x4700
	s_addc_u32 s19, s5, 0
	s_add_u32 s20, s4, 0x4800
	s_addc_u32 s21, s5, 0
	s_add_u32 s22, s4, 0x4900
	s_addc_u32 s23, s5, 0
	s_add_u32 s24, s4, 0x4a00
	s_addc_u32 s25, s5, 0
	s_add_u32 s26, s4, 0x4b00
	s_addc_u32 s27, s5, 0
	s_add_u32 s68, s4, 0x4c00
	s_addc_u32 s69, s5, 0
	s_add_u32 s70, s4, 0x4d00
	s_addc_u32 s71, s5, 0
	s_add_u32 s72, s4, 0x4e00
	s_addc_u32 s73, s5, 0
	s_add_u32 s74, s4, 0x4f00
	s_addc_u32 s75, s5, 0
	s_add_u32 s76, s4, 0x5000
	s_addc_u32 s77, s5, 0
	s_add_u32 s78, s4, 0x5100
	s_addc_u32 s79, s5, 0
	s_add_u32 s80, s4, 0x5200
	s_addc_u32 s81, s5, 0
	s_add_u32 s82, s4, 0x5300
	s_addc_u32 s83, s5, 0
	s_mov_b32 s35, 1
	s_branch .LBB0_1924

; #define LAS __attribute__((address_space(3)))
; __device__ __forceinline__ int get_tid() { int t = __builtin_amdgcn_workitem_id_x(); asm volatile("" : "+v"(t)); return t; }
; __device__ __forceinline__ unsigned xb_xcc_id() { return (unsigned)__builtin_amdgcn_s_getreg((3 << 11) | 20) & 0xFu; }
; __device__ __forceinline__ void xcd_barrier(unsigned* bar, volatile LAS unsigned* st) {
;     asm volatile("s_waitcnt vmcnt(0)" ::: "memory");
;     __syncthreads();
;     if (get_tid() == 0) {
;         const unsigned x = xb_xcc_id();
;         __builtin_amdgcn_s_waitcnt(0);
;         unsigned nloc = st[0], nx = st[1];
;         if (nloc == 0u) { xcd_barrier_complete(bar, x, nloc, nx); st[0] = nloc; st[1] = nx; }
.LBB0_2070:
	s_mov_b64 s[4:5], s[0:1]
	s_waitcnt lgkmcnt(0)
	s_load_dword s2, s[4:5], 0xd8
	s_add_i32 s35, s87, 8
	s_waitcnt lgkmcnt(0)
	s_cmp_gt_i32 s2, s31
	s_cbranch_scc1 .LBB0_2126
	s_load_dword s2, s[4:5], 0xdc
	s_waitcnt lgkmcnt(0)
	s_cmp_ge_i32 s35, s2
	s_cbranch_scc1 .LBB0_2126
	s_waitcnt vmcnt(0)
	s_waitcnt vmcnt(0)
	v_mov_b32_e32 v0, v206
	s_barrier
	s_nop 0
	v_cmp_eq_u32_e32 vcc, 0, v0
	s_and_saveexec_b64 s[2:3], vcc
	s_cbranch_execz .LBB0_2125
	buffer_inv sc1
	v_readlane_b32 s7, v255, 0
	s_load_dwordx2 s[4:5], s[4:5], 0xd0
	s_getreg_b32 s6, hwreg(HW_REG_XCC_ID, 0, 4)
	v_mov_b32_e32 v0, s7
	s_waitcnt lgkmcnt(0)
	ds_read_b32 v2, v0
	v_readlane_b32 s7, v255, 1
	s_and_b32 s10, s6, 15
	s_waitcnt lgkmcnt(0)
	v_cmp_ne_u32_e32 vcc, 0, v2
	v_mov_b32_e32 v0, s7
	ds_read_b32 v0, v0
	s_cbranch_vccnz .LBB0_2089
	s_add_u32 s6, s4, 0x4200
	s_addc_u32 s7, s5, 0
	s_add_u32 s12, s4, 0x4400
	s_addc_u32 s13, s5, 0
	s_add_u32 s14, s4, 0x4500
	s_addc_u32 s15, s5, 0
	s_add_u32 s16, s4, 0x4600
	s_addc_u32 s17, s5, 0
	s_add_u32 s18, s4, 0x4700
	s_addc_u32 s19, s5, 0
	s_add_u32 s20, s4, 0x4800
	s_addc_u32 s21, s5, 0
	s_add_u32 s22, s4, 0x4900
	s_addc_u32 s23, s5, 0
	s_add_u32 s24, s4, 0x4a00
	s_addc_u32 s25, s5, 0
	s_add_u32 s26, s4, 0x4b00
	s_addc_u32 s27, s5, 0
	s_add_u32 s68, s4, 0x4c00
	s_addc_u32 s69, s5, 0
	s_add_u32 s70, s4, 0x4d00
	s_addc_u32 s71, s5, 0
	s_add_u32 s72, s4, 0x4e00
	s_addc_u32 s73, s5, 0
	s_add_u32 s74, s4, 0x4f00
	s_addc_u32 s75, s5, 0
	s_add_u32 s76, s4, 0x5000
	s_addc_u32 s77, s5, 0
	s_add_u32 s78, s4, 0x5100
	s_addc_u32 s79, s5, 0
	s_add_u32 s80, s4, 0x5200
	s_addc_u32 s81, s5, 0
	s_add_u32 s82, s4, 0x5300
	s_addc_u32 s83, s5, 0
	s_mov_b32 s31, 1
	s_branch .LBB0_2076

; #define LAS __attribute__((address_space(3)))
; __device__ __forceinline__ int get_tid() { int t = __builtin_amdgcn_workitem_id_x(); asm volatile("" : "+v"(t)); return t; }
; __device__ __forceinline__ unsigned xb_xcc_id() { return (unsigned)__builtin_amdgcn_s_getreg((3 << 11) | 20) & 0xFu; }
; __device__ __forceinline__ void xcd_barrier(unsigned* bar, volatile LAS unsigned* st) {
;     asm volatile("s_waitcnt vmcnt(0)" ::: "memory");
;     __syncthreads();
;     if (get_tid() == 0) {
;         const unsigned x = xb_xcc_id();
;         __builtin_amdgcn_s_waitcnt(0);
;         unsigned nloc = st[0], nx = st[1];
;         if (nloc == 0u) { xcd_barrier_complete(bar, x, nloc, nx); st[0] = nloc; st[1] = nx; }
.LBB0_2147:
	s_mov_b64 s[4:5], s[0:1]
	s_load_dword s2, s[4:5], 0xd8
	s_add_i32 s31, s87, 9
	s_waitcnt lgkmcnt(0)
	s_cmp_gt_i32 s2, s35
	s_cbranch_scc1 .LBB0_2202
	s_load_dword s2, s[4:5], 0xdc
	s_waitcnt lgkmcnt(0)
	s_cmp_ge_i32 s31, s2
	s_cbranch_scc1 .LBB0_2202
	s_waitcnt vmcnt(0)
	s_waitcnt vmcnt(0)
	v_mov_b32_e32 v0, v206
	s_barrier
	s_nop 0
	v_cmp_eq_u32_e32 vcc, 0, v0
	s_and_saveexec_b64 s[2:3], vcc
	s_cbranch_execz .LBB0_2201
	buffer_inv sc1
	v_readlane_b32 s7, v255, 0
	s_load_dwordx2 s[4:5], s[4:5], 0xd0
	s_getreg_b32 s6, hwreg(HW_REG_XCC_ID, 0, 4)
	v_mov_b32_e32 v0, s7
	s_waitcnt lgkmcnt(0)
	ds_read_b32 v2, v0
	v_readlane_b32 s7, v255, 1
	s_and_b32 s10, s6, 15
	s_waitcnt lgkmcnt(0)
	v_cmp_ne_u32_e32 vcc, 0, v2
	v_mov_b32_e32 v0, s7
	ds_read_b32 v0, v0
	s_cbranch_vccnz .LBB0_2165
	s_add_u32 s6, s4, 0x4200
	s_addc_u32 s7, s5, 0
	s_add_u32 s12, s4, 0x4400
	s_addc_u32 s13, s5, 0
	s_add_u32 s14, s4, 0x4500
	s_addc_u32 s15, s5, 0
	s_add_u32 s16, s4, 0x4600
	s_addc_u32 s17, s5, 0
	s_add_u32 s18, s4, 0x4700
	s_addc_u32 s19, s5, 0
	s_add_u32 s20, s4, 0x4800
	s_addc_u32 s21, s5, 0
	s_add_u32 s22, s4, 0x4900
	s_addc_u32 s23, s5, 0
	s_add_u32 s24, s4, 0x4a00
	s_addc_u32 s25, s5, 0
	s_add_u32 s26, s4, 0x4b00
	s_addc_u32 s27, s5, 0
	s_add_u32 s68, s4, 0x4c00
	s_addc_u32 s69, s5, 0
	s_add_u32 s70, s4, 0x4d00
	s_addc_u32 s71, s5, 0
	s_add_u32 s72, s4, 0x4e00
	s_addc_u32 s73, s5, 0
	s_add_u32 s74, s4, 0x4f00
	s_addc_u32 s75, s5, 0
	s_add_u32 s76, s4, 0x5000
	s_addc_u32 s77, s5, 0
	s_add_u32 s78, s4, 0x5100
	s_addc_u32 s79, s5, 0
	s_add_u32 s80, s4, 0x5200
	s_addc_u32 s81, s5, 0
	s_add_u32 s82, s4, 0x5300
	s_addc_u32 s83, s5, 0
	s_mov_b32 s35, 1
	s_branch .LBB0_2153

; #define LAS __attribute__((address_space(3)))
; __device__ __forceinline__ int get_tid() { int t = __builtin_amdgcn_workitem_id_x(); asm volatile("" : "+v"(t)); return t; }
; __device__ __forceinline__ unsigned xb_xcc_id() { return (unsigned)__builtin_amdgcn_s_getreg((3 << 11) | 20) & 0xFu; }
; __device__ __forceinline__ void xcd_barrier(unsigned* bar, volatile LAS unsigned* st) {
;     asm volatile("s_waitcnt vmcnt(0)" ::: "memory");
;     __syncthreads();
;     if (get_tid() == 0) {
;         const unsigned x = xb_xcc_id();
;         __builtin_amdgcn_s_waitcnt(0);
;         unsigned nloc = st[0], nx = st[1];
;         if (nloc == 0u) { xcd_barrier_complete(bar, x, nloc, nx); st[0] = nloc; st[1] = nx; }
.LBB0_2933:
	s_mov_b64 s[4:5], s[0:1]
	s_load_dword s2, s[4:5], 0xd8
	s_add_i32 s54, s87, 10
	s_waitcnt lgkmcnt(0)
	s_cmp_gt_i32 s2, s31
	s_cbranch_scc1 .LBB0_2988
	s_load_dword s2, s[4:5], 0xdc
	s_waitcnt lgkmcnt(0)
	s_cmp_ge_i32 s54, s2
	s_cbranch_scc1 .LBB0_2988
	s_waitcnt vmcnt(0)
	s_waitcnt vmcnt(0)
	v_mov_b32_e32 v0, v206
	s_barrier
	s_nop 0
	v_cmp_eq_u32_e32 vcc, 0, v0
	s_and_saveexec_b64 s[2:3], vcc
	s_cbranch_execz .LBB0_2987
	buffer_inv sc1
	v_readlane_b32 s7, v255, 0
	s_load_dwordx2 s[4:5], s[4:5], 0xd0
	s_getreg_b32 s6, hwreg(HW_REG_XCC_ID, 0, 4)
	v_mov_b32_e32 v0, s7
	s_waitcnt lgkmcnt(0)
	ds_read_b32 v2, v0
	v_readlane_b32 s7, v255, 1
	s_and_b32 s10, s6, 15
	s_waitcnt lgkmcnt(0)
	v_cmp_ne_u32_e32 vcc, 0, v2
	v_mov_b32_e32 v0, s7
	ds_read_b32 v0, v0
	s_cbranch_vccnz .LBB0_2951
	s_add_u32 s6, s4, 0x4200
	s_addc_u32 s7, s5, 0
	s_add_u32 s12, s4, 0x4400
	s_addc_u32 s13, s5, 0
	s_add_u32 s14, s4, 0x4500
	s_addc_u32 s15, s5, 0
	s_add_u32 s16, s4, 0x4600
	s_addc_u32 s17, s5, 0
	s_add_u32 s18, s4, 0x4700
	s_addc_u32 s19, s5, 0
	s_add_u32 s20, s4, 0x4800
	s_addc_u32 s21, s5, 0
	s_add_u32 s22, s4, 0x4900
	s_addc_u32 s23, s5, 0
	s_add_u32 s24, s4, 0x4a00
	s_addc_u32 s25, s5, 0
	s_add_u32 s26, s4, 0x4b00
	s_addc_u32 s27, s5, 0
	s_add_u32 s68, s4, 0x4c00
	s_addc_u32 s69, s5, 0
	s_add_u32 s70, s4, 0x4d00
	s_addc_u32 s71, s5, 0
	s_add_u32 s72, s4, 0x4e00
	s_addc_u32 s73, s5, 0
	s_add_u32 s74, s4, 0x4f00
	s_addc_u32 s75, s5, 0
	s_add_u32 s76, s4, 0x5000
	s_addc_u32 s77, s5, 0
	s_add_u32 s78, s4, 0x5100
	s_addc_u32 s79, s5, 0
	s_add_u32 s80, s4, 0x5200
	s_addc_u32 s81, s5, 0
	s_add_u32 s82, s4, 0x5300
	s_addc_u32 s83, s5, 0
	s_mov_b32 s31, 1
	s_branch .LBB0_2939

; #define LAS __attribute__((address_space(3)))
; __device__ __forceinline__ int get_tid() { int t = __builtin_amdgcn_workitem_id_x(); asm volatile("" : "+v"(t)); return t; }
; __device__ __forceinline__ unsigned xb_xcc_id() { return (unsigned)__builtin_amdgcn_s_getreg((3 << 11) | 20) & 0xFu; }
; __device__ __forceinline__ void xcd_barrier(unsigned* bar, volatile LAS unsigned* st) {
;     asm volatile("s_waitcnt vmcnt(0)" ::: "memory");
;     __syncthreads();
;     if (get_tid() == 0) {
;         const unsigned x = xb_xcc_id();
;         __builtin_amdgcn_s_waitcnt(0);
;         unsigned nloc = st[0], nx = st[1];
;         if (nloc == 0u) { xcd_barrier_complete(bar, x, nloc, nx); st[0] = nloc; st[1] = nx; }
.LBB0_3388:
	buffer_inv sc1
	v_readlane_b32 s7, v255, 0
	s_load_dwordx2 s[4:5], s[4:5], 0xd0
	s_getreg_b32 s6, hwreg(HW_REG_XCC_ID, 0, 4)
	v_mov_b32_e32 v0, s7
	s_waitcnt lgkmcnt(0)
	ds_read_b32 v2, v0
	v_readlane_b32 s7, v255, 1
	s_and_b32 s10, s6, 15
	s_waitcnt lgkmcnt(0)
	v_cmp_ne_u32_e32 vcc, 0, v2
	v_mov_b32_e32 v0, s7
	ds_read_b32 v0, v0
	s_cbranch_vccnz .LBB0_3404
	s_add_u32 s6, s4, 0x4200
	s_addc_u32 s7, s5, 0
	s_add_u32 s12, s4, 0x4400
	s_addc_u32 s13, s5, 0
	s_add_u32 s14, s4, 0x4500
	s_addc_u32 s15, s5, 0
	s_add_u32 s16, s4, 0x4600
	s_addc_u32 s17, s5, 0
	s_add_u32 s18, s4, 0x4700
	s_addc_u32 s19, s5, 0
	s_add_u32 s20, s4, 0x4800
	s_addc_u32 s21, s5, 0
	s_add_u32 s22, s4, 0x4900
	s_addc_u32 s23, s5, 0
	s_add_u32 s24, s4, 0x4a00
	s_addc_u32 s25, s5, 0
	s_add_u32 s26, s4, 0x4b00
	s_addc_u32 s27, s5, 0
	s_add_u32 s66, s4, 0x4c00
	s_addc_u32 s67, s5, 0
	s_add_u32 s68, s4, 0x4d00
	s_addc_u32 s69, s5, 0
	s_add_u32 s70, s4, 0x4e00
	s_addc_u32 s71, s5, 0
	s_add_u32 s72, s4, 0x4f00
	s_addc_u32 s73, s5, 0
	s_add_u32 s74, s4, 0x5000
	s_addc_u32 s75, s5, 0
	s_add_u32 s76, s4, 0x5100
	s_addc_u32 s77, s5, 0
	s_add_u32 s78, s4, 0x5200
	s_addc_u32 s79, s5, 0
	s_add_u32 s80, s4, 0x5300
	s_addc_u32 s81, s5, 0
	s_mov_b32 s30, 1
	s_branch .LBB0_3392

; __device__ __forceinline__ unsigned xb_ld(unsigned* p)              { return __hip_atomic_load(p, __ATOMIC_RELAXED, __HIP_MEMORY_SCOPE_AGENT); }
; __device__ __forceinline__ unsigned xb_add(unsigned* p, unsigned v) { return __hip_atomic_fetch_add(p, v, __ATOMIC_RELAXED, __HIP_MEMORY_SCOPE_AGENT); }
; #define XB_SPIN(cond, bar) do { unsigned _sp = 0; while (cond) { __builtin_amdgcn_s_sleep(1); \
;     if ((++_sp & 255u) == 0u) { if (xb_ld(&(bar)[XB_TMO])) break; if (_sp > XB_SPIN_CAP) { atomicAdd(&(bar)[XB_TMO], 1u); break; } } } } while (0)
; __device__ __forceinline__ void xcd_barrier(unsigned* bar, volatile LAS unsigned* st) {
;     ...
;         const unsigned old = xb_add(&bar[XB_XSUB(x)], 1u);
;         const unsigned gen = old / nloc;
;         if (old + 1u == (gen + 1u) * nloc) {
;             __builtin_amdgcn_fence(__ATOMIC_RELEASE, "agent");
;             asm volatile("s_waitcnt vmcnt(0)" ::: "memory");
;             const unsigned og = xb_add(&bar[XB_TOP], 1u);
;             const unsigned tg = og / nx;
;             if (og + 1u == (tg + 1u) * nx) xb_add(&bar[XB_TOPGEN], 1u);
;             else XB_SPIN(xb_ld(&bar[XB_TOPGEN]) == tg, bar);
;             __builtin_amdgcn_fence(__ATOMIC_ACQUIRE, "agent");
;             xb_add(&bar[XB_XGEN(x)], 1u);
;             asm volatile("s_waitcnt vmcnt(0)" ::: "memory");
.LBB0_3437:
	s_or_b64 exec, exec, s[4:5]
	s_mov_b64 s[4:5], exec
	v_mbcnt_lo_u32_b32 v0, s4, 0
	v_mbcnt_hi_u32_b32 v0, s5, v0
	v_cmp_eq_u32_e32 vcc, 0, v0
	s_waitcnt vmcnt(0)
	s_and_saveexec_b64 s[12:13], vcc
	s_cbranch_execnz .LBB0_3438
	s_getpc_b64 s[98:99]
